# v12 + every bf16 K-loop head aligned to 64 bytes (code placement)
# speedup vs baseline: 1.0198x; 1.0198x over previous
.LBB0_640:
	s_lshl_b32 s65, s64, 21
	s_andn2_b64 vcc, exec, s[40:41]
	s_lshl_b32 s66, s63, 21
	s_cbranch_vccnz .LBB0_648
	s_and_b64 s[18:19], s[4:5], exec
	v_mov_b32_e32 v2, 0
	s_cselect_b32 s69, s65, s71
	s_cselect_b32 s70, s66, s72
	s_add_i32 s71, s71, 0x180080
	s_addk_i32 s72, 0x100
	s_mov_b32 s73, 0
	v_mov_b32_e32 v3, v2
	v_mov_b32_e32 v4, v2
	v_mov_b32_e32 v5, v2
	s_waitcnt vmcnt(35)
	v_mov_b32_e32 v10, v2
	v_mov_b32_e32 v11, v2
	v_mov_b32_e32 v12, v2
	v_mov_b32_e32 v13, v2
	s_waitcnt vmcnt(33)
	v_mov_b32_e32 v18, v2
	v_mov_b32_e32 v19, v2
	v_mov_b32_e32 v20, v2
	v_mov_b32_e32 v21, v2
	s_waitcnt vmcnt(31)
	v_mov_b32_e32 v26, v2
	v_mov_b32_e32 v27, v2
	v_mov_b32_e32 v28, v2
	v_mov_b32_e32 v29, v2
	s_waitcnt vmcnt(29)
	v_mov_b32_e32 v34, v2
	v_mov_b32_e32 v35, v2
	v_mov_b32_e32 v36, v2
	v_mov_b32_e32 v37, v2
	s_waitcnt vmcnt(27)
	v_mov_b32_e32 v42, v2
	v_mov_b32_e32 v43, v2
	v_mov_b32_e32 v44, v2
	v_mov_b32_e32 v45, v2
	s_waitcnt vmcnt(25)
	v_mov_b32_e32 v50, v2
	v_mov_b32_e32 v51, v2
	v_mov_b32_e32 v52, v2
	v_mov_b32_e32 v53, v2
	s_waitcnt vmcnt(23)
	v_mov_b32_e32 v58, v2
	v_mov_b32_e32 v59, v2
	v_mov_b32_e32 v60, v2
	v_mov_b32_e32 v61, v2
	v_mov_b32_e32 v6, v2
	v_mov_b32_e32 v7, v2
	v_mov_b32_e32 v8, v2
	v_mov_b32_e32 v9, v2
	v_mov_b32_e32 v14, v2
	v_mov_b32_e32 v15, v2
	v_mov_b32_e32 v16, v2
	v_mov_b32_e32 v17, v2
	v_mov_b32_e32 v22, v2
	v_mov_b32_e32 v23, v2
	v_mov_b32_e32 v24, v2
	v_mov_b32_e32 v25, v2
	v_mov_b32_e32 v30, v2
	v_mov_b32_e32 v31, v2
	v_mov_b32_e32 v32, v2
	v_mov_b32_e32 v33, v2
	v_mov_b32_e32 v38, v2
	v_mov_b32_e32 v39, v2
	v_mov_b32_e32 v40, v2
	v_mov_b32_e32 v41, v2
	v_mov_b32_e32 v46, v2
	v_mov_b32_e32 v47, v2
	v_mov_b32_e32 v48, v2
	v_mov_b32_e32 v49, v2
	v_mov_b32_e32 v54, v2
	v_mov_b32_e32 v55, v2
	v_mov_b32_e32 v56, v2
	v_mov_b32_e32 v57, v2
	s_waitcnt vmcnt(22)
	v_mov_b32_e32 v62, v2
	v_mov_b32_e32 v63, v2
	v_mov_b32_e32 v64, v2
	v_mov_b32_e32 v65, v2
	v_mov_b32_e32 v70, v2
	v_mov_b32_e32 v71, v2
	v_mov_b32_e32 v72, v2
	v_mov_b32_e32 v73, v2
	v_mov_b32_e32 v74, v2
	v_mov_b32_e32 v75, v2
	v_mov_b32_e32 v76, v2
	v_mov_b32_e32 v77, v2
	v_mov_b32_e32 v82, v2
	v_mov_b32_e32 v83, v2
	v_mov_b32_e32 v84, v2
	v_mov_b32_e32 v85, v2
	v_mov_b32_e32 v90, v2
	v_mov_b32_e32 v91, v2
	v_mov_b32_e32 v92, v2
	v_mov_b32_e32 v93, v2
	v_mov_b32_e32 v98, v2
	v_mov_b32_e32 v99, v2
	v_mov_b32_e32 v100, v2
	v_mov_b32_e32 v101, v2
	v_mov_b32_e32 v106, v2
	v_mov_b32_e32 v107, v2
	v_mov_b32_e32 v108, v2
	v_mov_b32_e32 v109, v2
	v_mov_b32_e32 v122, v2
	v_mov_b32_e32 v123, v2
	v_mov_b32_e32 v124, v2
	v_mov_b32_e32 v125, v2
	v_mov_b32_e32 v126, v2
	v_mov_b32_e32 v127, v2
	v_mov_b32_e32 v128, v2
	v_mov_b32_e32 v129, v2
	v_mov_b32_e32 v66, v2
	v_mov_b32_e32 v67, v2
	v_mov_b32_e32 v68, v2
	v_mov_b32_e32 v69, v2
	v_mov_b32_e32 v78, v2
	v_mov_b32_e32 v79, v2
	v_mov_b32_e32 v80, v2
	v_mov_b32_e32 v81, v2
	v_mov_b32_e32 v86, v2
	v_mov_b32_e32 v87, v2
	v_mov_b32_e32 v88, v2
	v_mov_b32_e32 v89, v2
	v_mov_b32_e32 v94, v2
	v_mov_b32_e32 v95, v2
	v_mov_b32_e32 v96, v2
	v_mov_b32_e32 v97, v2
	v_mov_b32_e32 v102, v2
	v_mov_b32_e32 v103, v2
	v_mov_b32_e32 v104, v2
	v_mov_b32_e32 v105, v2
	v_mov_b32_e32 v110, v2
	v_mov_b32_e32 v111, v2
	v_mov_b32_e32 v112, v2
	v_mov_b32_e32 v113, v2
	v_mov_b32_e32 v114, v2
	v_mov_b32_e32 v115, v2
	v_mov_b32_e32 v116, v2
	v_mov_b32_e32 v117, v2
	v_mov_b32_e32 v118, v2
	v_mov_b32_e32 v119, v2
	v_mov_b32_e32 v120, v2
	v_mov_b32_e32 v121, v2
	.p2align	6

.LBB0_797:
	s_mul_i32 s73, s72, 0x560000
	s_andn2_b64 vcc, exec, s[36:37]
	s_mul_i32 s74, s71, 0x560000
	s_cbranch_vccnz .LBB0_823
	s_and_b64 s[6:7], s[4:5], exec
	v_mov_b32_e32 v2, 0
	s_cselect_b32 s6, s73, s77
	s_cselect_b32 s7, s74, s78
	s_add_i32 s77, s77, 0x408080
	s_addk_i32 s78, 0x100
	s_mov_b32 s79, 0
	s_waitcnt lgkmcnt(0)
	v_mov_b32_e32 v3, v2
	v_mov_b32_e32 v4, v2
	v_mov_b32_e32 v5, v2
	v_mov_b32_e32 v6, v2
	v_mov_b32_e32 v7, v2
	v_mov_b32_e32 v8, v2
	v_mov_b32_e32 v9, v2
	s_waitcnt vmcnt(35)
	v_mov_b32_e32 v10, v2
	v_mov_b32_e32 v11, v2
	v_mov_b32_e32 v12, v2
	v_mov_b32_e32 v13, v2
	s_waitcnt vmcnt(34)
	v_mov_b32_e32 v14, v2
	v_mov_b32_e32 v15, v2
	v_mov_b32_e32 v16, v2
	v_mov_b32_e32 v17, v2
	s_waitcnt vmcnt(32)
	v_mov_b32_e32 v22, v2
	v_mov_b32_e32 v23, v2
	v_mov_b32_e32 v24, v2
	v_mov_b32_e32 v25, v2
	s_waitcnt vmcnt(30)
	v_mov_b32_e32 v30, v2
	v_mov_b32_e32 v31, v2
	v_mov_b32_e32 v32, v2
	v_mov_b32_e32 v33, v2
	s_waitcnt vmcnt(28)
	v_mov_b32_e32 v38, v2
	v_mov_b32_e32 v39, v2
	v_mov_b32_e32 v40, v2
	v_mov_b32_e32 v41, v2
	s_waitcnt vmcnt(26)
	v_mov_b32_e32 v46, v2
	v_mov_b32_e32 v47, v2
	v_mov_b32_e32 v48, v2
	v_mov_b32_e32 v49, v2
	v_mov_b32_e32 v18, v2
	v_mov_b32_e32 v19, v2
	v_mov_b32_e32 v20, v2
	v_mov_b32_e32 v21, v2
	v_mov_b32_e32 v26, v2
	v_mov_b32_e32 v27, v2
	v_mov_b32_e32 v28, v2
	v_mov_b32_e32 v29, v2
	v_mov_b32_e32 v34, v2
	v_mov_b32_e32 v35, v2
	v_mov_b32_e32 v36, v2
	v_mov_b32_e32 v37, v2
	v_mov_b32_e32 v42, v2
	v_mov_b32_e32 v43, v2
	v_mov_b32_e32 v44, v2
	v_mov_b32_e32 v45, v2
	s_waitcnt vmcnt(25)
	v_mov_b32_e32 v50, v2
	v_mov_b32_e32 v51, v2
	v_mov_b32_e32 v52, v2
	v_mov_b32_e32 v53, v2
	s_waitcnt vmcnt(24)
	v_mov_b32_e32 v54, v2
	v_mov_b32_e32 v55, v2
	v_mov_b32_e32 v56, v2
	v_mov_b32_e32 v57, v2
	s_waitcnt vmcnt(23)
	v_mov_b32_e32 v58, v2
	v_mov_b32_e32 v59, v2
	v_mov_b32_e32 v60, v2
	v_mov_b32_e32 v61, v2
	s_waitcnt vmcnt(22)
	v_mov_b32_e32 v62, v2
	v_mov_b32_e32 v63, v2
	v_mov_b32_e32 v64, v2
	v_mov_b32_e32 v65, v2
	v_mov_b32_e32 v66, v2
	v_mov_b32_e32 v67, v2
	v_mov_b32_e32 v68, v2
	v_mov_b32_e32 v69, v2
	v_mov_b32_e32 v70, v2
	v_mov_b32_e32 v71, v2
	v_mov_b32_e32 v72, v2
	v_mov_b32_e32 v73, v2
	v_mov_b32_e32 v74, v2
	v_mov_b32_e32 v75, v2
	v_mov_b32_e32 v76, v2
	v_mov_b32_e32 v77, v2
	v_mov_b32_e32 v78, v2
	v_mov_b32_e32 v79, v2
	v_mov_b32_e32 v80, v2
	v_mov_b32_e32 v81, v2
	v_mov_b32_e32 v86, v2
	v_mov_b32_e32 v87, v2
	v_mov_b32_e32 v88, v2
	v_mov_b32_e32 v89, v2
	v_mov_b32_e32 v94, v2
	v_mov_b32_e32 v95, v2
	v_mov_b32_e32 v96, v2
	v_mov_b32_e32 v97, v2
	v_mov_b32_e32 v102, v2
	v_mov_b32_e32 v103, v2
	v_mov_b32_e32 v104, v2
	v_mov_b32_e32 v105, v2
	v_mov_b32_e32 v110, v2
	v_mov_b32_e32 v111, v2
	v_mov_b32_e32 v112, v2
	v_mov_b32_e32 v113, v2
	v_mov_b32_e32 v82, v2
	v_mov_b32_e32 v83, v2
	v_mov_b32_e32 v84, v2
	v_mov_b32_e32 v85, v2
	v_mov_b32_e32 v90, v2
	v_mov_b32_e32 v91, v2
	v_mov_b32_e32 v92, v2
	v_mov_b32_e32 v93, v2
	v_mov_b32_e32 v98, v2
	v_mov_b32_e32 v99, v2
	v_mov_b32_e32 v100, v2
	v_mov_b32_e32 v101, v2
	v_mov_b32_e32 v106, v2
	v_mov_b32_e32 v107, v2
	v_mov_b32_e32 v108, v2
	v_mov_b32_e32 v109, v2
	v_mov_b32_e32 v114, v2
	v_mov_b32_e32 v115, v2
	v_mov_b32_e32 v116, v2
	v_mov_b32_e32 v117, v2
	v_mov_b32_e32 v118, v2
	v_mov_b32_e32 v119, v2
	v_mov_b32_e32 v120, v2
	v_mov_b32_e32 v121, v2
	v_mov_b32_e32 v122, v2
	v_mov_b32_e32 v123, v2
	v_mov_b32_e32 v124, v2
	v_mov_b32_e32 v125, v2
	v_mov_b32_e32 v126, v2
	v_mov_b32_e32 v127, v2
	v_mov_b32_e32 v128, v2
	v_mov_b32_e32 v129, v2
	.p2align	6

.LBB0_890:
	s_lshl_b32 s85, s31, 21
	s_andn2_b64 vcc, exec, s[46:47]
	s_lshl_b32 s86, s30, 21
	s_cbranch_vccnz .LBB0_940
	s_and_b64 s[6:7], s[4:5], exec
	v_mov_b32_e32 v2, 0
	s_cselect_b32 s6, s85, s8
	s_cselect_b32 s7, s86, s9
	s_add_i32 s8, s8, 0x180080
	s_addk_i32 s9, 0x100
	s_mov_b32 s52, 0
	v_mov_b32_e32 v3, v2
	v_mov_b32_e32 v4, v2
	v_mov_b32_e32 v5, v2
	s_waitcnt vmcnt(35)
	v_mov_b32_e32 v10, v2
	v_mov_b32_e32 v11, v2
	v_mov_b32_e32 v12, v2
	v_mov_b32_e32 v13, v2
	s_waitcnt vmcnt(33)
	v_mov_b32_e32 v18, v2
	v_mov_b32_e32 v19, v2
	v_mov_b32_e32 v20, v2
	v_mov_b32_e32 v21, v2
	s_waitcnt vmcnt(31)
	v_mov_b32_e32 v26, v2
	v_mov_b32_e32 v27, v2
	v_mov_b32_e32 v28, v2
	v_mov_b32_e32 v29, v2
	s_waitcnt vmcnt(29)
	v_mov_b32_e32 v34, v2
	v_mov_b32_e32 v35, v2
	v_mov_b32_e32 v36, v2
	v_mov_b32_e32 v37, v2
	s_waitcnt vmcnt(27)
	v_mov_b32_e32 v42, v2
	v_mov_b32_e32 v43, v2
	v_mov_b32_e32 v44, v2
	v_mov_b32_e32 v45, v2
	s_waitcnt vmcnt(25)
	v_mov_b32_e32 v50, v2
	v_mov_b32_e32 v51, v2
	v_mov_b32_e32 v52, v2
	v_mov_b32_e32 v53, v2
	s_waitcnt vmcnt(23)
	v_mov_b32_e32 v58, v2
	v_mov_b32_e32 v59, v2
	v_mov_b32_e32 v60, v2
	v_mov_b32_e32 v61, v2
	v_mov_b32_e32 v6, v2
	v_mov_b32_e32 v7, v2
	v_mov_b32_e32 v8, v2
	v_mov_b32_e32 v9, v2
	v_mov_b32_e32 v14, v2
	v_mov_b32_e32 v15, v2
	v_mov_b32_e32 v16, v2
	v_mov_b32_e32 v17, v2
	v_mov_b32_e32 v22, v2
	v_mov_b32_e32 v23, v2
	v_mov_b32_e32 v24, v2
	v_mov_b32_e32 v25, v2
	v_mov_b32_e32 v30, v2
	v_mov_b32_e32 v31, v2
	v_mov_b32_e32 v32, v2
	v_mov_b32_e32 v33, v2
	v_mov_b32_e32 v38, v2
	v_mov_b32_e32 v39, v2
	v_mov_b32_e32 v40, v2
	v_mov_b32_e32 v41, v2
	v_mov_b32_e32 v46, v2
	v_mov_b32_e32 v47, v2
	v_mov_b32_e32 v48, v2
	v_mov_b32_e32 v49, v2
	v_mov_b32_e32 v54, v2
	v_mov_b32_e32 v55, v2
	v_mov_b32_e32 v56, v2
	v_mov_b32_e32 v57, v2
	s_waitcnt vmcnt(22)
	v_mov_b32_e32 v62, v2
	v_mov_b32_e32 v63, v2
	v_mov_b32_e32 v64, v2
	v_mov_b32_e32 v65, v2
	v_mov_b32_e32 v66, v2
	v_mov_b32_e32 v67, v2
	v_mov_b32_e32 v68, v2
	v_mov_b32_e32 v69, v2
	v_mov_b32_e32 v74, v2
	v_mov_b32_e32 v75, v2
	v_mov_b32_e32 v76, v2
	v_mov_b32_e32 v77, v2
	v_mov_b32_e32 v82, v2
	v_mov_b32_e32 v83, v2
	v_mov_b32_e32 v84, v2
	v_mov_b32_e32 v85, v2
	v_mov_b32_e32 v86, v2
	v_mov_b32_e32 v87, v2
	v_mov_b32_e32 v88, v2
	v_mov_b32_e32 v89, v2
	v_mov_b32_e32 v98, v2
	v_mov_b32_e32 v99, v2
	v_mov_b32_e32 v100, v2
	v_mov_b32_e32 v101, v2
	v_mov_b32_e32 v106, v2
	v_mov_b32_e32 v107, v2
	v_mov_b32_e32 v108, v2
	v_mov_b32_e32 v109, v2
	v_mov_b32_e32 v114, v2
	v_mov_b32_e32 v115, v2
	v_mov_b32_e32 v116, v2
	v_mov_b32_e32 v117, v2
	v_mov_b32_e32 v122, v2
	v_mov_b32_e32 v123, v2
	v_mov_b32_e32 v124, v2
	v_mov_b32_e32 v125, v2
	v_mov_b32_e32 v70, v2
	v_mov_b32_e32 v71, v2
	v_mov_b32_e32 v72, v2
	v_mov_b32_e32 v73, v2
	v_mov_b32_e32 v78, v2
	v_mov_b32_e32 v79, v2
	v_mov_b32_e32 v80, v2
	v_mov_b32_e32 v81, v2
	v_mov_b32_e32 v90, v2
	v_mov_b32_e32 v91, v2
	v_mov_b32_e32 v92, v2
	v_mov_b32_e32 v93, v2
	v_mov_b32_e32 v94, v2
	v_mov_b32_e32 v95, v2
	v_mov_b32_e32 v96, v2
	v_mov_b32_e32 v97, v2
	v_mov_b32_e32 v102, v2
	v_mov_b32_e32 v103, v2
	v_mov_b32_e32 v104, v2
	v_mov_b32_e32 v105, v2
	v_mov_b32_e32 v110, v2
	v_mov_b32_e32 v111, v2
	v_mov_b32_e32 v112, v2
	v_mov_b32_e32 v113, v2
	v_mov_b32_e32 v118, v2
	v_mov_b32_e32 v119, v2
	v_mov_b32_e32 v120, v2
	v_mov_b32_e32 v121, v2
	v_mov_b32_e32 v126, v2
	v_mov_b32_e32 v127, v2
	v_mov_b32_e32 v128, v2
	v_mov_b32_e32 v129, v2
	.p2align	6

.LBB0_1018:
	s_add_i32 s6, s84, s86
	s_andn2_b64 vcc, exec, s[52:53]
	s_lshl_b32 s85, s6, 18
	s_cbranch_vccnz .LBB0_1026
	s_and_b64 s[6:7], s[56:57], exec
	v_mov_b32_e32 v2, 0
	s_cselect_b32 s87, s85, s88
	s_addk_i32 s88, 0x100
	s_mov_b32 s6, 0
	s_mov_b32 s89, 0
	v_mov_b32_e32 v3, v2
	v_mov_b32_e32 v4, v2
	v_mov_b32_e32 v5, v2
	v_mov_b32_e32 v6, v2
	v_mov_b32_e32 v7, v2
	v_mov_b32_e32 v8, v2
	v_mov_b32_e32 v9, v2
	v_mov_b32_e32 v18, v2
	v_mov_b32_e32 v19, v2
	v_mov_b32_e32 v20, v2
	v_mov_b32_e32 v21, v2
	v_mov_b32_e32 v22, v2
	v_mov_b32_e32 v23, v2
	v_mov_b32_e32 v24, v2
	v_mov_b32_e32 v25, v2
	v_mov_b32_e32 v34, v2
	v_mov_b32_e32 v35, v2
	v_mov_b32_e32 v36, v2
	v_mov_b32_e32 v37, v2
	v_mov_b32_e32 v38, v2
	v_mov_b32_e32 v39, v2
	v_mov_b32_e32 v40, v2
	v_mov_b32_e32 v41, v2
	v_mov_b32_e32 v50, v2
	v_mov_b32_e32 v51, v2
	v_mov_b32_e32 v52, v2
	v_mov_b32_e32 v53, v2
	v_mov_b32_e32 v54, v2
	v_mov_b32_e32 v55, v2
	v_mov_b32_e32 v56, v2
	v_mov_b32_e32 v57, v2
	v_mov_b32_e32 v10, v2
	v_mov_b32_e32 v11, v2
	v_mov_b32_e32 v12, v2
	v_mov_b32_e32 v13, v2
	v_mov_b32_e32 v14, v2
	v_mov_b32_e32 v15, v2
	v_mov_b32_e32 v16, v2
	v_mov_b32_e32 v17, v2
	v_mov_b32_e32 v26, v2
	v_mov_b32_e32 v27, v2
	v_mov_b32_e32 v28, v2
	v_mov_b32_e32 v29, v2
	v_mov_b32_e32 v30, v2
	v_mov_b32_e32 v31, v2
	v_mov_b32_e32 v32, v2
	v_mov_b32_e32 v33, v2
	v_mov_b32_e32 v42, v2
	v_mov_b32_e32 v43, v2
	v_mov_b32_e32 v44, v2
	v_mov_b32_e32 v45, v2
	v_mov_b32_e32 v46, v2
	v_mov_b32_e32 v47, v2
	v_mov_b32_e32 v48, v2
	v_mov_b32_e32 v49, v2
	v_mov_b32_e32 v58, v2
	v_mov_b32_e32 v59, v2
	v_mov_b32_e32 v60, v2
	v_mov_b32_e32 v61, v2
	v_mov_b32_e32 v62, v2
	v_mov_b32_e32 v63, v2
	v_mov_b32_e32 v64, v2
	v_mov_b32_e32 v65, v2
	v_mov_b32_e32 v66, v2
	v_mov_b32_e32 v67, v2
	v_mov_b32_e32 v68, v2
	v_mov_b32_e32 v69, v2
	v_mov_b32_e32 v70, v2
	v_mov_b32_e32 v71, v2
	v_mov_b32_e32 v72, v2
	v_mov_b32_e32 v73, v2
	v_mov_b32_e32 v82, v2
	v_mov_b32_e32 v83, v2
	v_mov_b32_e32 v84, v2
	v_mov_b32_e32 v85, v2
	v_mov_b32_e32 v86, v2
	v_mov_b32_e32 v87, v2
	v_mov_b32_e32 v88, v2
	v_mov_b32_e32 v89, v2
	v_mov_b32_e32 v98, v2
	v_mov_b32_e32 v99, v2
	v_mov_b32_e32 v100, v2
	v_mov_b32_e32 v101, v2
	v_mov_b32_e32 v102, v2
	v_mov_b32_e32 v103, v2
	v_mov_b32_e32 v104, v2
	v_mov_b32_e32 v105, v2
	v_mov_b32_e32 v114, v2
	v_mov_b32_e32 v115, v2
	v_mov_b32_e32 v116, v2
	v_mov_b32_e32 v117, v2
	v_mov_b32_e32 v118, v2
	v_mov_b32_e32 v119, v2
	v_mov_b32_e32 v120, v2
	v_mov_b32_e32 v121, v2
	v_mov_b32_e32 v74, v2
	v_mov_b32_e32 v75, v2
	v_mov_b32_e32 v76, v2
	v_mov_b32_e32 v77, v2
	v_mov_b32_e32 v78, v2
	v_mov_b32_e32 v79, v2
	v_mov_b32_e32 v80, v2
	v_mov_b32_e32 v81, v2
	v_mov_b32_e32 v90, v2
	v_mov_b32_e32 v91, v2
	v_mov_b32_e32 v92, v2
	v_mov_b32_e32 v93, v2
	v_mov_b32_e32 v94, v2
	v_mov_b32_e32 v95, v2
	v_mov_b32_e32 v96, v2
	v_mov_b32_e32 v97, v2
	v_mov_b32_e32 v106, v2
	v_mov_b32_e32 v107, v2
	v_mov_b32_e32 v108, v2
	v_mov_b32_e32 v109, v2
	v_mov_b32_e32 v110, v2
	v_mov_b32_e32 v111, v2
	v_mov_b32_e32 v112, v2
	v_mov_b32_e32 v113, v2
	v_mov_b32_e32 v122, v2
	v_mov_b32_e32 v123, v2
	v_mov_b32_e32 v124, v2
	v_mov_b32_e32 v125, v2
	v_mov_b32_e32 v126, v2
	v_mov_b32_e32 v127, v2
	v_mov_b32_e32 v128, v2
	v_mov_b32_e32 v129, v2
	.p2align	6

.LBB0_1033:
	s_add_i32 s58, s58, 1
	s_lshr_b32 s40, s58, 1
	s_mul_i32 s40, s40, s33
	s_add_i32 s62, s40, s2
	s_cmpk_lt_i32 s62, 0x200
	s_cselect_b64 s[40:41], -1, 0
	s_ashr_i32 s59, s62, 6
	s_and_b32 s63, s58, 1
	s_and_b32 s61, s62, 63
	s_lshl_b32 s64, s59, 23
	s_lshl_b32 s69, s63, 26
	s_mul_i32 s62, s62, 0x60000
	s_lshl_b32 s68, s61, 9
	s_add_i32 s64, s64, s69
	s_bitset1_b32 s62, 10
	s_or_b32 s64, s64, s68
	s_and_b64 vcc, exec, s[4:5]
	v_mov_b32_e32 v129, 0
	v_mov_b32_e32 v128, 0
	v_mov_b32_e32 v127, 0
	v_mov_b32_e32 v126, 0
	v_mov_b32_e32 v125, 0
	v_mov_b32_e32 v124, 0
	v_mov_b32_e32 v123, 0
	v_mov_b32_e32 v122, 0
	v_mov_b32_e32 v113, 0
	v_mov_b32_e32 v112, 0
	v_mov_b32_e32 v111, 0
	v_mov_b32_e32 v110, 0
	v_mov_b32_e32 v109, 0
	v_mov_b32_e32 v108, 0
	v_mov_b32_e32 v107, 0
	v_mov_b32_e32 v106, 0
	v_mov_b32_e32 v97, 0
	v_mov_b32_e32 v96, 0
	v_mov_b32_e32 v95, 0
	v_mov_b32_e32 v94, 0
	v_mov_b32_e32 v93, 0
	v_mov_b32_e32 v92, 0
	v_mov_b32_e32 v91, 0
	v_mov_b32_e32 v90, 0
	v_mov_b32_e32 v81, 0
	v_mov_b32_e32 v80, 0
	v_mov_b32_e32 v79, 0
	v_mov_b32_e32 v78, 0
	v_mov_b32_e32 v77, 0
	v_mov_b32_e32 v76, 0
	v_mov_b32_e32 v75, 0
	v_mov_b32_e32 v74, 0
	v_mov_b32_e32 v121, 0
	v_mov_b32_e32 v120, 0
	v_mov_b32_e32 v119, 0
	v_mov_b32_e32 v118, 0
	v_mov_b32_e32 v117, 0
	v_mov_b32_e32 v116, 0
	v_mov_b32_e32 v115, 0
	v_mov_b32_e32 v114, 0
	v_mov_b32_e32 v105, 0
	v_mov_b32_e32 v104, 0
	v_mov_b32_e32 v103, 0
	v_mov_b32_e32 v102, 0
	v_mov_b32_e32 v101, 0
	v_mov_b32_e32 v100, 0
	v_mov_b32_e32 v99, 0
	v_mov_b32_e32 v98, 0
	v_mov_b32_e32 v89, 0
	v_mov_b32_e32 v88, 0
	v_mov_b32_e32 v87, 0
	v_mov_b32_e32 v86, 0
	v_mov_b32_e32 v85, 0
	v_mov_b32_e32 v84, 0
	v_mov_b32_e32 v83, 0
	v_mov_b32_e32 v82, 0
	v_mov_b32_e32 v73, 0
	v_mov_b32_e32 v72, 0
	v_mov_b32_e32 v71, 0
	v_mov_b32_e32 v70, 0
	v_mov_b32_e32 v69, 0
	v_mov_b32_e32 v68, 0
	v_mov_b32_e32 v67, 0
	v_mov_b32_e32 v66, 0
	v_mov_b32_e32 v65, 0
	v_mov_b32_e32 v64, 0
	v_mov_b32_e32 v63, 0
	v_mov_b32_e32 v62, 0
	v_mov_b32_e32 v61, 0
	v_mov_b32_e32 v60, 0
	v_mov_b32_e32 v59, 0
	v_mov_b32_e32 v58, 0
	v_mov_b32_e32 v49, 0
	v_mov_b32_e32 v48, 0
	v_mov_b32_e32 v47, 0
	v_mov_b32_e32 v46, 0
	v_mov_b32_e32 v45, 0
	v_mov_b32_e32 v44, 0
	v_mov_b32_e32 v43, 0
	v_mov_b32_e32 v42, 0
	v_mov_b32_e32 v33, 0
	v_mov_b32_e32 v32, 0
	v_mov_b32_e32 v31, 0
	v_mov_b32_e32 v30, 0
	v_mov_b32_e32 v29, 0
	v_mov_b32_e32 v28, 0
	v_mov_b32_e32 v27, 0
	v_mov_b32_e32 v26, 0
	v_mov_b32_e32 v17, 0
	v_mov_b32_e32 v16, 0
	v_mov_b32_e32 v15, 0
	v_mov_b32_e32 v14, 0
	v_mov_b32_e32 v13, 0
	v_mov_b32_e32 v12, 0
	v_mov_b32_e32 v11, 0
	v_mov_b32_e32 v10, 0
	v_mov_b32_e32 v57, 0
	v_mov_b32_e32 v56, 0
	v_mov_b32_e32 v55, 0
	v_mov_b32_e32 v54, 0
	v_mov_b32_e32 v53, 0
	v_mov_b32_e32 v52, 0
	v_mov_b32_e32 v51, 0
	v_mov_b32_e32 v50, 0
	v_mov_b32_e32 v41, 0
	v_mov_b32_e32 v40, 0
	v_mov_b32_e32 v39, 0
	v_mov_b32_e32 v38, 0
	v_mov_b32_e32 v37, 0
	v_mov_b32_e32 v36, 0
	v_mov_b32_e32 v35, 0
	v_mov_b32_e32 v34, 0
	v_mov_b32_e32 v25, 0
	v_mov_b32_e32 v24, 0
	v_mov_b32_e32 v23, 0
	v_mov_b32_e32 v22, 0
	v_mov_b32_e32 v21, 0
	v_mov_b32_e32 v20, 0
	v_mov_b32_e32 v19, 0
	v_mov_b32_e32 v18, 0
	v_mov_b32_e32 v9, 0
	v_mov_b32_e32 v8, 0
	v_mov_b32_e32 v7, 0
	v_mov_b32_e32 v6, 0
	v_mov_b32_e32 v5, 0
	v_mov_b32_e32 v4, 0
	v_mov_b32_e32 v3, 0
	v_mov_b32_e32 v2, 0
	s_cbranch_vccnz .LBB0_1036
	s_and_b64 s[68:69], s[40:41], exec
	v_mov_b32_e32 v2, 0
	s_cselect_b32 s68, s62, s70
	s_cselect_b32 s69, s64, s71
	s_add_i32 s70, s70, 0x48080
	s_addk_i32 s71, 0x100
	s_mov_b32 s72, 0
	v_mov_b32_e32 v3, v2
	v_mov_b32_e32 v4, v2
	v_mov_b32_e32 v5, v2
	v_mov_b32_e32 v6, v2
	v_mov_b32_e32 v7, v2
	v_mov_b32_e32 v8, v2
	v_mov_b32_e32 v9, v2
	v_mov_b32_e32 v18, v2
	v_mov_b32_e32 v19, v2
	v_mov_b32_e32 v20, v2
	v_mov_b32_e32 v21, v2
	v_mov_b32_e32 v22, v2
	v_mov_b32_e32 v23, v2
	v_mov_b32_e32 v24, v2
	v_mov_b32_e32 v25, v2
	v_mov_b32_e32 v34, v2
	v_mov_b32_e32 v35, v2
	v_mov_b32_e32 v36, v2
	v_mov_b32_e32 v37, v2
	v_mov_b32_e32 v38, v2
	v_mov_b32_e32 v39, v2
	v_mov_b32_e32 v40, v2
	v_mov_b32_e32 v41, v2
	v_mov_b32_e32 v50, v2
	v_mov_b32_e32 v51, v2
	v_mov_b32_e32 v52, v2
	v_mov_b32_e32 v53, v2
	v_mov_b32_e32 v54, v2
	v_mov_b32_e32 v55, v2
	v_mov_b32_e32 v56, v2
	v_mov_b32_e32 v57, v2
	v_mov_b32_e32 v10, v2
	v_mov_b32_e32 v11, v2
	v_mov_b32_e32 v12, v2
	v_mov_b32_e32 v13, v2
	v_mov_b32_e32 v14, v2
	v_mov_b32_e32 v15, v2
	v_mov_b32_e32 v16, v2
	v_mov_b32_e32 v17, v2
	v_mov_b32_e32 v26, v2
	v_mov_b32_e32 v27, v2
	v_mov_b32_e32 v28, v2
	v_mov_b32_e32 v29, v2
	v_mov_b32_e32 v30, v2
	v_mov_b32_e32 v31, v2
	v_mov_b32_e32 v32, v2
	v_mov_b32_e32 v33, v2
	v_mov_b32_e32 v42, v2
	v_mov_b32_e32 v43, v2
	v_mov_b32_e32 v44, v2
	v_mov_b32_e32 v45, v2
	v_mov_b32_e32 v46, v2
	v_mov_b32_e32 v47, v2
	v_mov_b32_e32 v48, v2
	v_mov_b32_e32 v49, v2
	v_mov_b32_e32 v58, v2
	v_mov_b32_e32 v59, v2
	v_mov_b32_e32 v60, v2
	v_mov_b32_e32 v61, v2
	v_mov_b32_e32 v62, v2
	v_mov_b32_e32 v63, v2
	v_mov_b32_e32 v64, v2
	v_mov_b32_e32 v65, v2
	v_mov_b32_e32 v66, v2
	v_mov_b32_e32 v67, v2
	v_mov_b32_e32 v68, v2
	v_mov_b32_e32 v69, v2
	v_mov_b32_e32 v70, v2
	v_mov_b32_e32 v71, v2
	v_mov_b32_e32 v72, v2
	v_mov_b32_e32 v73, v2
	v_mov_b32_e32 v82, v2
	v_mov_b32_e32 v83, v2
	v_mov_b32_e32 v84, v2
	v_mov_b32_e32 v85, v2
	v_mov_b32_e32 v86, v2
	v_mov_b32_e32 v87, v2
	v_mov_b32_e32 v88, v2
	v_mov_b32_e32 v89, v2
	v_mov_b32_e32 v98, v2
	v_mov_b32_e32 v99, v2
	v_mov_b32_e32 v100, v2
	v_mov_b32_e32 v101, v2
	v_mov_b32_e32 v102, v2
	v_mov_b32_e32 v103, v2
	v_mov_b32_e32 v104, v2
	v_mov_b32_e32 v105, v2
	v_mov_b32_e32 v114, v2
	v_mov_b32_e32 v115, v2
	v_mov_b32_e32 v116, v2
	v_mov_b32_e32 v117, v2
	v_mov_b32_e32 v118, v2
	v_mov_b32_e32 v119, v2
	v_mov_b32_e32 v120, v2
	v_mov_b32_e32 v121, v2
	v_mov_b32_e32 v74, v2
	v_mov_b32_e32 v75, v2
	v_mov_b32_e32 v76, v2
	v_mov_b32_e32 v77, v2
	v_mov_b32_e32 v78, v2
	v_mov_b32_e32 v79, v2
	v_mov_b32_e32 v80, v2
	v_mov_b32_e32 v81, v2
	v_mov_b32_e32 v90, v2
	v_mov_b32_e32 v91, v2
	v_mov_b32_e32 v92, v2
	v_mov_b32_e32 v93, v2
	v_mov_b32_e32 v94, v2
	v_mov_b32_e32 v95, v2
	v_mov_b32_e32 v96, v2
	v_mov_b32_e32 v97, v2
	v_mov_b32_e32 v106, v2
	v_mov_b32_e32 v107, v2
	v_mov_b32_e32 v108, v2
	v_mov_b32_e32 v109, v2
	v_mov_b32_e32 v110, v2
	v_mov_b32_e32 v111, v2
	v_mov_b32_e32 v112, v2
	v_mov_b32_e32 v113, v2
	v_mov_b32_e32 v122, v2
	v_mov_b32_e32 v123, v2
	v_mov_b32_e32 v124, v2
	v_mov_b32_e32 v125, v2
	v_mov_b32_e32 v126, v2
	v_mov_b32_e32 v127, v2
	v_mov_b32_e32 v128, v2
	v_mov_b32_e32 v129, v2
	.p2align	6

.LBB0_1048:
	s_add_i32 s41, s41, 1
	s_mul_i32 s18, s41, s33
	s_add_i32 s18, s18, s2
	s_mov_b32 s35, s58
	s_mov_b32 s59, s57
	s_ashr_i32 s57, s18, 6
	s_and_b32 s58, s18, 63
	s_cmpk_lt_i32 s18, 0x200
	s_cselect_b64 s[36:37], -1, 0
	s_and_b64 s[18:19], s[36:37], exec
	s_cselect_b32 s18, s57, s59
	s_cselect_b32 s19, s58, s35
	s_lshl_b32 s59, s18, 9
	s_lshl_b32 s18, s19, 20
	s_add_i32 s59, s59, s18
	s_and_b64 vcc, exec, s[4:5]
	v_mov_b32_e32 v129, 0
	v_mov_b32_e32 v128, 0
	v_mov_b32_e32 v127, 0
	v_mov_b32_e32 v126, 0
	v_mov_b32_e32 v125, 0
	v_mov_b32_e32 v124, 0
	v_mov_b32_e32 v123, 0
	v_mov_b32_e32 v122, 0
	v_mov_b32_e32 v113, 0
	v_mov_b32_e32 v112, 0
	v_mov_b32_e32 v111, 0
	v_mov_b32_e32 v110, 0
	v_mov_b32_e32 v109, 0
	v_mov_b32_e32 v108, 0
	v_mov_b32_e32 v107, 0
	v_mov_b32_e32 v106, 0
	v_mov_b32_e32 v97, 0
	s_waitcnt vmcnt(24)
	v_mov_b32_e32 v96, 0
	v_mov_b32_e32 v95, 0
	v_mov_b32_e32 v94, 0
	v_mov_b32_e32 v93, 0
	v_mov_b32_e32 v92, 0
	v_mov_b32_e32 v91, 0
	v_mov_b32_e32 v90, 0
	v_mov_b32_e32 v81, 0
	v_mov_b32_e32 v80, 0
	v_mov_b32_e32 v79, 0
	v_mov_b32_e32 v78, 0
	v_mov_b32_e32 v77, 0
	v_mov_b32_e32 v76, 0
	v_mov_b32_e32 v75, 0
	v_mov_b32_e32 v74, 0
	v_mov_b32_e32 v121, 0
	v_mov_b32_e32 v120, 0
	v_mov_b32_e32 v119, 0
	v_mov_b32_e32 v118, 0
	v_mov_b32_e32 v117, 0
	v_mov_b32_e32 v116, 0
	v_mov_b32_e32 v115, 0
	v_mov_b32_e32 v114, 0
	v_mov_b32_e32 v105, 0
	v_mov_b32_e32 v104, 0
	v_mov_b32_e32 v103, 0
	s_waitcnt vmcnt(23)
	v_mov_b32_e32 v102, 0
	v_mov_b32_e32 v101, 0
	s_waitcnt vmcnt(22)
	v_mov_b32_e32 v100, 0
	v_mov_b32_e32 v99, 0
	v_mov_b32_e32 v98, 0
	v_mov_b32_e32 v89, 0
	v_mov_b32_e32 v88, 0
	v_mov_b32_e32 v87, 0
	v_mov_b32_e32 v86, 0
	v_mov_b32_e32 v85, 0
	v_mov_b32_e32 v84, 0
	v_mov_b32_e32 v83, 0
	v_mov_b32_e32 v82, 0
	v_mov_b32_e32 v73, 0
	v_mov_b32_e32 v72, 0
	v_mov_b32_e32 v71, 0
	v_mov_b32_e32 v70, 0
	v_mov_b32_e32 v69, 0
	v_mov_b32_e32 v68, 0
	v_mov_b32_e32 v67, 0
	v_mov_b32_e32 v66, 0
	v_mov_b32_e32 v65, 0
	v_mov_b32_e32 v64, 0
	v_mov_b32_e32 v63, 0
	v_mov_b32_e32 v62, 0
	v_mov_b32_e32 v61, 0
	v_mov_b32_e32 v60, 0
	v_mov_b32_e32 v59, 0
	v_mov_b32_e32 v58, 0
	v_mov_b32_e32 v49, 0
	v_mov_b32_e32 v48, 0
	v_mov_b32_e32 v47, 0
	v_mov_b32_e32 v46, 0
	v_mov_b32_e32 v45, 0
	v_mov_b32_e32 v44, 0
	v_mov_b32_e32 v43, 0
	v_mov_b32_e32 v42, 0
	v_mov_b32_e32 v33, 0
	v_mov_b32_e32 v32, 0
	v_mov_b32_e32 v31, 0
	v_mov_b32_e32 v30, 0
	v_mov_b32_e32 v29, 0
	v_mov_b32_e32 v28, 0
	v_mov_b32_e32 v27, 0
	v_mov_b32_e32 v26, 0
	v_mov_b32_e32 v17, 0
	v_mov_b32_e32 v16, 0
	v_mov_b32_e32 v15, 0
	v_mov_b32_e32 v14, 0
	v_mov_b32_e32 v13, 0
	v_mov_b32_e32 v12, 0
	v_mov_b32_e32 v11, 0
	v_mov_b32_e32 v10, 0
	v_mov_b32_e32 v57, 0
	v_mov_b32_e32 v56, 0
	v_mov_b32_e32 v55, 0
	v_mov_b32_e32 v54, 0
	v_mov_b32_e32 v53, 0
	v_mov_b32_e32 v52, 0
	v_mov_b32_e32 v51, 0
	v_mov_b32_e32 v50, 0
	v_mov_b32_e32 v41, 0
	v_mov_b32_e32 v40, 0
	v_mov_b32_e32 v39, 0
	v_mov_b32_e32 v38, 0
	v_mov_b32_e32 v37, 0
	v_mov_b32_e32 v36, 0
	v_mov_b32_e32 v35, 0
	v_mov_b32_e32 v34, 0
	v_mov_b32_e32 v25, 0
	v_mov_b32_e32 v24, 0
	v_mov_b32_e32 v23, 0
	v_mov_b32_e32 v22, 0
	v_mov_b32_e32 v21, 0
	v_mov_b32_e32 v20, 0
	v_mov_b32_e32 v19, 0
	v_mov_b32_e32 v18, 0
	v_mov_b32_e32 v9, 0
	v_mov_b32_e32 v8, 0
	v_mov_b32_e32 v7, 0
	v_mov_b32_e32 v6, 0
	v_mov_b32_e32 v5, 0
	v_mov_b32_e32 v4, 0
	v_mov_b32_e32 v3, 0
	v_mov_b32_e32 v2, 0
	s_cbranch_vccnz .LBB0_1051
	s_and_b64 s[18:19], s[36:37], exec
	v_mov_b32_e32 v2, 0
	s_cselect_b32 s35, s59, s61
	s_add_i32 s61, s61, 0xc0080
	s_mov_b32 s62, 0
	v_mov_b32_e32 v3, v2
	v_mov_b32_e32 v4, v2
	v_mov_b32_e32 v5, v2
	v_mov_b32_e32 v6, v2
	v_mov_b32_e32 v7, v2
	v_mov_b32_e32 v8, v2
	v_mov_b32_e32 v9, v2
	v_mov_b32_e32 v18, v2
	v_mov_b32_e32 v19, v2
	v_mov_b32_e32 v20, v2
	v_mov_b32_e32 v21, v2
	v_mov_b32_e32 v22, v2
	v_mov_b32_e32 v23, v2
	v_mov_b32_e32 v24, v2
	v_mov_b32_e32 v25, v2
	v_mov_b32_e32 v34, v2
	v_mov_b32_e32 v35, v2
	v_mov_b32_e32 v36, v2
	v_mov_b32_e32 v37, v2
	v_mov_b32_e32 v38, v2
	v_mov_b32_e32 v39, v2
	v_mov_b32_e32 v40, v2
	v_mov_b32_e32 v41, v2
	v_mov_b32_e32 v50, v2
	v_mov_b32_e32 v51, v2
	v_mov_b32_e32 v52, v2
	v_mov_b32_e32 v53, v2
	v_mov_b32_e32 v54, v2
	v_mov_b32_e32 v55, v2
	v_mov_b32_e32 v56, v2
	v_mov_b32_e32 v57, v2
	v_mov_b32_e32 v10, v2
	v_mov_b32_e32 v11, v2
	v_mov_b32_e32 v12, v2
	v_mov_b32_e32 v13, v2
	v_mov_b32_e32 v14, v2
	v_mov_b32_e32 v15, v2
	v_mov_b32_e32 v16, v2
	v_mov_b32_e32 v17, v2
	v_mov_b32_e32 v26, v2
	v_mov_b32_e32 v27, v2
	v_mov_b32_e32 v28, v2
	v_mov_b32_e32 v29, v2
	v_mov_b32_e32 v30, v2
	v_mov_b32_e32 v31, v2
	v_mov_b32_e32 v32, v2
	v_mov_b32_e32 v33, v2
	v_mov_b32_e32 v42, v2
	v_mov_b32_e32 v43, v2
	v_mov_b32_e32 v44, v2
	v_mov_b32_e32 v45, v2
	v_mov_b32_e32 v46, v2
	v_mov_b32_e32 v47, v2
	v_mov_b32_e32 v48, v2
	v_mov_b32_e32 v49, v2
	v_mov_b32_e32 v58, v2
	v_mov_b32_e32 v59, v2
	v_mov_b32_e32 v60, v2
	v_mov_b32_e32 v61, v2
	v_mov_b32_e32 v62, v2
	v_mov_b32_e32 v63, v2
	v_mov_b32_e32 v64, v2
	v_mov_b32_e32 v65, v2
	v_mov_b32_e32 v66, v2
	v_mov_b32_e32 v67, v2
	v_mov_b32_e32 v68, v2
	v_mov_b32_e32 v69, v2
	v_mov_b32_e32 v70, v2
	v_mov_b32_e32 v71, v2
	v_mov_b32_e32 v72, v2
	v_mov_b32_e32 v73, v2
	v_mov_b32_e32 v82, v2
	v_mov_b32_e32 v83, v2
	v_mov_b32_e32 v84, v2
	v_mov_b32_e32 v85, v2
	v_mov_b32_e32 v86, v2
	v_mov_b32_e32 v87, v2
	v_mov_b32_e32 v88, v2
	v_mov_b32_e32 v89, v2
	v_mov_b32_e32 v98, v2
	v_mov_b32_e32 v99, v2
	v_mov_b32_e32 v100, v2
	v_mov_b32_e32 v101, v2
	v_mov_b32_e32 v102, v2
	v_mov_b32_e32 v103, v2
	v_mov_b32_e32 v104, v2
	v_mov_b32_e32 v105, v2
	v_mov_b32_e32 v114, v2
	v_mov_b32_e32 v115, v2
	v_mov_b32_e32 v116, v2
	v_mov_b32_e32 v117, v2
	v_mov_b32_e32 v118, v2
	v_mov_b32_e32 v119, v2
	v_mov_b32_e32 v120, v2
	v_mov_b32_e32 v121, v2
	v_mov_b32_e32 v74, v2
	v_mov_b32_e32 v75, v2
	v_mov_b32_e32 v76, v2
	v_mov_b32_e32 v77, v2
	v_mov_b32_e32 v78, v2
	v_mov_b32_e32 v79, v2
	v_mov_b32_e32 v80, v2
	v_mov_b32_e32 v81, v2
	v_mov_b32_e32 v90, v2
	v_mov_b32_e32 v91, v2
	v_mov_b32_e32 v92, v2
	v_mov_b32_e32 v93, v2
	v_mov_b32_e32 v94, v2
	v_mov_b32_e32 v95, v2
	v_mov_b32_e32 v96, v2
	v_mov_b32_e32 v97, v2
	v_mov_b32_e32 v106, v2
	v_mov_b32_e32 v107, v2
	v_mov_b32_e32 v108, v2
	v_mov_b32_e32 v109, v2
	v_mov_b32_e32 v110, v2
	v_mov_b32_e32 v111, v2
	v_mov_b32_e32 v112, v2
	v_mov_b32_e32 v113, v2
	v_mov_b32_e32 v122, v2
	v_mov_b32_e32 v123, v2
	v_mov_b32_e32 v124, v2
	v_mov_b32_e32 v125, v2
	v_mov_b32_e32 v126, v2
	v_mov_b32_e32 v127, v2
	v_mov_b32_e32 v128, v2
	v_mov_b32_e32 v129, v2
	.p2align	6

.LBB0_1179:
	s_add_i32 s58, s58, 1
	s_mul_i32 s18, s58, s33
	s_add_i32 s84, s18, s2
	s_mov_b32 s47, s82
	s_mov_b32 s48, s81
	s_ashr_i32 s81, s84, 6
	s_and_b32 s82, s84, 63
	s_cmpk_lt_i32 s84, 0x200
	s_cselect_b64 s[44:45], -1, 0
	s_and_b64 s[18:19], s[44:45], exec
	s_cselect_b32 s18, s81, s48
	s_cselect_b32 s19, s82, s47
	s_lshl_b32 s83, s18, 9
	s_lshl_b32 s18, s19, 20
	s_add_i32 s83, s83, s18
	s_mul_i32 s84, s84, 0x60000
	s_and_b64 vcc, exec, s[4:5]
	v_mov_b32_e32 v133, 0
	v_mov_b32_e32 v132, 0
	v_mov_b32_e32 v131, 0
	v_mov_b32_e32 v130, 0
	v_mov_b32_e32 v129, 0
	v_mov_b32_e32 v128, 0
	v_mov_b32_e32 v127, 0
	v_mov_b32_e32 v126, 0
	v_mov_b32_e32 v117, 0
	v_mov_b32_e32 v116, 0
	v_mov_b32_e32 v115, 0
	v_mov_b32_e32 v114, 0
	v_mov_b32_e32 v113, 0
	v_mov_b32_e32 v112, 0
	v_mov_b32_e32 v111, 0
	v_mov_b32_e32 v110, 0
	v_mov_b32_e32 v101, 0
	s_waitcnt vmcnt(22)
	v_mov_b32_e32 v100, 0
	v_mov_b32_e32 v99, 0
	v_mov_b32_e32 v98, 0
	v_mov_b32_e32 v97, 0
	v_mov_b32_e32 v96, 0
	v_mov_b32_e32 v95, 0
	v_mov_b32_e32 v94, 0
	v_mov_b32_e32 v85, 0
	v_mov_b32_e32 v84, 0
	v_mov_b32_e32 v83, 0
	v_mov_b32_e32 v82, 0
	v_mov_b32_e32 v81, 0
	v_mov_b32_e32 v80, 0
	v_mov_b32_e32 v79, 0
	v_mov_b32_e32 v78, 0
	v_mov_b32_e32 v125, 0
	v_mov_b32_e32 v124, 0
	v_mov_b32_e32 v123, 0
	v_mov_b32_e32 v122, 0
	v_mov_b32_e32 v121, 0
	v_mov_b32_e32 v120, 0
	v_mov_b32_e32 v119, 0
	v_mov_b32_e32 v118, 0
	v_mov_b32_e32 v109, 0
	v_mov_b32_e32 v108, 0
	v_mov_b32_e32 v107, 0
	v_mov_b32_e32 v106, 0
	v_mov_b32_e32 v105, 0
	v_mov_b32_e32 v104, 0
	v_mov_b32_e32 v103, 0
	v_mov_b32_e32 v102, 0
	v_mov_b32_e32 v93, 0
	v_mov_b32_e32 v92, 0
	v_mov_b32_e32 v91, 0
	v_mov_b32_e32 v90, 0
	v_mov_b32_e32 v89, 0
	v_mov_b32_e32 v88, 0
	v_mov_b32_e32 v87, 0
	v_mov_b32_e32 v86, 0
	v_mov_b32_e32 v77, 0
	v_mov_b32_e32 v76, 0
	v_mov_b32_e32 v75, 0
	v_mov_b32_e32 v74, 0
	v_mov_b32_e32 v73, 0
	v_mov_b32_e32 v72, 0
	v_mov_b32_e32 v71, 0
	v_mov_b32_e32 v70, 0
	v_mov_b32_e32 v69, 0
	v_mov_b32_e32 v68, 0
	v_mov_b32_e32 v67, 0
	v_mov_b32_e32 v66, 0
	v_mov_b32_e32 v65, 0
	v_mov_b32_e32 v64, 0
	v_mov_b32_e32 v63, 0
	v_mov_b32_e32 v62, 0
	v_mov_b32_e32 v53, 0
	v_mov_b32_e32 v52, 0
	v_mov_b32_e32 v51, 0
	v_mov_b32_e32 v50, 0
	v_mov_b32_e32 v49, 0
	v_mov_b32_e32 v48, 0
	v_mov_b32_e32 v47, 0
	v_mov_b32_e32 v46, 0
	v_mov_b32_e32 v37, 0
	v_mov_b32_e32 v36, 0
	v_mov_b32_e32 v35, 0
	v_mov_b32_e32 v34, 0
	v_mov_b32_e32 v33, 0
	v_mov_b32_e32 v32, 0
	v_mov_b32_e32 v31, 0
	v_mov_b32_e32 v30, 0
	v_mov_b32_e32 v21, 0
	v_mov_b32_e32 v20, 0
	v_mov_b32_e32 v19, 0
	v_mov_b32_e32 v18, 0
	v_mov_b32_e32 v17, 0
	v_mov_b32_e32 v16, 0
	v_mov_b32_e32 v15, 0
	v_mov_b32_e32 v14, 0
	v_mov_b32_e32 v61, 0
	v_mov_b32_e32 v60, 0
	v_mov_b32_e32 v59, 0
	v_mov_b32_e32 v58, 0
	v_mov_b32_e32 v57, 0
	v_mov_b32_e32 v56, 0
	v_mov_b32_e32 v55, 0
	v_mov_b32_e32 v54, 0
	v_mov_b32_e32 v45, 0
	v_mov_b32_e32 v44, 0
	v_mov_b32_e32 v43, 0
	v_mov_b32_e32 v42, 0
	v_mov_b32_e32 v41, 0
	v_mov_b32_e32 v40, 0
	v_mov_b32_e32 v39, 0
	v_mov_b32_e32 v38, 0
	v_mov_b32_e32 v29, 0
	v_mov_b32_e32 v28, 0
	v_mov_b32_e32 v27, 0
	v_mov_b32_e32 v26, 0
	v_mov_b32_e32 v25, 0
	v_mov_b32_e32 v24, 0
	v_mov_b32_e32 v23, 0
	v_mov_b32_e32 v22, 0
	v_mov_b32_e32 v13, 0
	v_mov_b32_e32 v12, 0
	v_mov_b32_e32 v11, 0
	v_mov_b32_e32 v10, 0
	v_mov_b32_e32 v9, 0
	v_mov_b32_e32 v8, 0
	v_mov_b32_e32 v7, 0
	v_mov_b32_e32 v6, 0
	s_cbranch_vccnz .LBB0_1193
	s_and_b64 s[18:19], s[44:45], exec
	s_cselect_b32 s87, s83, s86
	s_cselect_b32 s88, s84, s50
	s_ashr_i32 s47, s46, 31
	s_add_i32 s89, s86, 0x80
	s_lshl_b64 s[18:19], s[46:47], 2
	v_mov_b32_e32 v4, v3
	v_mov_b32_e32 v5, v3
	s_add_u32 s48, s60, s18
	v_mov_b32_e32 v2, v3
	v_mov_b64_e32 v[8:9], v[4:5]
	v_mov_b64_e32 v[12:13], v[4:5]
	v_mov_b64_e32 v[24:25], v[4:5]
	v_mov_b64_e32 v[28:29], v[4:5]
	v_mov_b64_e32 v[40:41], v[4:5]
	v_mov_b64_e32 v[44:45], v[4:5]
	v_mov_b64_e32 v[56:57], v[4:5]
	v_mov_b64_e32 v[60:61], v[4:5]
	v_mov_b64_e32 v[16:17], v[4:5]
	v_mov_b64_e32 v[20:21], v[4:5]
	v_mov_b64_e32 v[32:33], v[4:5]
	v_mov_b64_e32 v[36:37], v[4:5]
	v_mov_b64_e32 v[48:49], v[4:5]
	v_mov_b64_e32 v[52:53], v[4:5]
	v_mov_b64_e32 v[64:65], v[4:5]
	v_mov_b64_e32 v[68:69], v[4:5]
	v_mov_b64_e32 v[72:73], v[4:5]
	v_mov_b64_e32 v[76:77], v[4:5]
	v_mov_b64_e32 v[88:89], v[4:5]
	v_mov_b64_e32 v[92:93], v[4:5]
	v_mov_b64_e32 v[104:105], v[4:5]
	v_mov_b64_e32 v[108:109], v[4:5]
	v_mov_b64_e32 v[120:121], v[4:5]
	v_mov_b64_e32 v[124:125], v[4:5]
	v_mov_b64_e32 v[80:81], v[4:5]
	v_mov_b64_e32 v[84:85], v[4:5]
	v_mov_b64_e32 v[96:97], v[4:5]
	v_mov_b64_e32 v[100:101], v[4:5]
	v_mov_b64_e32 v[112:113], v[4:5]
	v_mov_b64_e32 v[116:117], v[4:5]
	v_mov_b64_e32 v[128:129], v[4:5]
	v_mov_b64_e32 v[132:133], v[4:5]
	s_addc_u32 s49, s61, s19
	s_add_i32 s47, s50, 0x100
	s_mov_b32 s90, 0
	v_mov_b64_e32 v[6:7], v[2:3]
	v_mov_b64_e32 v[10:11], v[2:3]
	v_mov_b64_e32 v[22:23], v[2:3]
	v_mov_b64_e32 v[26:27], v[2:3]
	v_mov_b64_e32 v[38:39], v[2:3]
	v_mov_b64_e32 v[42:43], v[2:3]
	v_mov_b64_e32 v[54:55], v[2:3]
	v_mov_b64_e32 v[58:59], v[2:3]
	v_mov_b64_e32 v[14:15], v[2:3]
	v_mov_b64_e32 v[18:19], v[2:3]
	v_mov_b64_e32 v[30:31], v[2:3]
	v_mov_b64_e32 v[34:35], v[2:3]
	v_mov_b64_e32 v[46:47], v[2:3]
	v_mov_b64_e32 v[50:51], v[2:3]
	v_mov_b64_e32 v[62:63], v[2:3]
	v_mov_b64_e32 v[66:67], v[2:3]
	v_mov_b64_e32 v[70:71], v[2:3]
	v_mov_b64_e32 v[74:75], v[2:3]
	v_mov_b64_e32 v[86:87], v[2:3]
	v_mov_b64_e32 v[90:91], v[2:3]
	v_mov_b64_e32 v[102:103], v[2:3]
	v_mov_b64_e32 v[106:107], v[2:3]
	v_mov_b64_e32 v[118:119], v[2:3]
	v_mov_b64_e32 v[122:123], v[2:3]
	v_mov_b64_e32 v[78:79], v[2:3]
	v_mov_b64_e32 v[82:83], v[2:3]
	v_mov_b64_e32 v[94:95], v[2:3]
	v_mov_b64_e32 v[98:99], v[2:3]
	v_mov_b64_e32 v[110:111], v[2:3]
	v_mov_b64_e32 v[114:115], v[2:3]
	v_mov_b64_e32 v[126:127], v[2:3]
	v_mov_b64_e32 v[130:131], v[2:3]
	s_mov_b32 s91, 0
	s_branch .LBB0_1182
	.p2align	6

.LBB0_1288:
	s_lshl_b32 s68, s67, 21
	s_andn2_b64 vcc, exec, s[36:37]
	s_lshl_b32 s69, s66, 21
	s_cbranch_vccnz .LBB0_1314
	s_and_b64 s[6:7], s[4:5], exec
	v_mov_b32_e32 v2, 0
	s_cselect_b32 s6, s68, s72
	s_cselect_b32 s7, s69, s73
	s_add_i32 s72, s72, 0x180080
	s_addk_i32 s73, 0x100
	s_mov_b32 s74, 0
	s_waitcnt lgkmcnt(0)
	v_mov_b32_e32 v3, v2
	v_mov_b32_e32 v4, v2
	v_mov_b32_e32 v5, v2
	v_mov_b32_e32 v6, v2
	v_mov_b32_e32 v7, v2
	v_mov_b32_e32 v8, v2
	v_mov_b32_e32 v9, v2
	s_waitcnt vmcnt(33)
	v_mov_b32_e32 v18, v2
	v_mov_b32_e32 v19, v2
	v_mov_b32_e32 v20, v2
	v_mov_b32_e32 v21, v2
	s_waitcnt vmcnt(32)
	v_mov_b32_e32 v22, v2
	v_mov_b32_e32 v23, v2
	v_mov_b32_e32 v24, v2
	v_mov_b32_e32 v25, v2
	s_waitcnt vmcnt(29)
	v_mov_b32_e32 v34, v2
	v_mov_b32_e32 v35, v2
	v_mov_b32_e32 v36, v2
	v_mov_b32_e32 v37, v2
	s_waitcnt vmcnt(28)
	v_mov_b32_e32 v38, v2
	v_mov_b32_e32 v39, v2
	v_mov_b32_e32 v40, v2
	v_mov_b32_e32 v41, v2
	s_waitcnt vmcnt(25)
	v_mov_b32_e32 v50, v2
	v_mov_b32_e32 v51, v2
	v_mov_b32_e32 v52, v2
	v_mov_b32_e32 v53, v2
	s_waitcnt vmcnt(24)
	v_mov_b32_e32 v54, v2
	v_mov_b32_e32 v55, v2
	v_mov_b32_e32 v56, v2
	v_mov_b32_e32 v57, v2
	v_mov_b32_e32 v10, v2
	v_mov_b32_e32 v11, v2
	v_mov_b32_e32 v12, v2
	v_mov_b32_e32 v13, v2
	v_mov_b32_e32 v14, v2
	v_mov_b32_e32 v15, v2
	v_mov_b32_e32 v16, v2
	v_mov_b32_e32 v17, v2
	v_mov_b32_e32 v26, v2
	v_mov_b32_e32 v27, v2
	v_mov_b32_e32 v28, v2
	v_mov_b32_e32 v29, v2
	v_mov_b32_e32 v30, v2
	v_mov_b32_e32 v31, v2
	v_mov_b32_e32 v32, v2
	v_mov_b32_e32 v33, v2
	v_mov_b32_e32 v42, v2
	v_mov_b32_e32 v43, v2
	v_mov_b32_e32 v44, v2
	v_mov_b32_e32 v45, v2
	v_mov_b32_e32 v46, v2
	v_mov_b32_e32 v47, v2
	v_mov_b32_e32 v48, v2
	v_mov_b32_e32 v49, v2
	s_waitcnt vmcnt(23)
	v_mov_b32_e32 v58, v2
	v_mov_b32_e32 v59, v2
	v_mov_b32_e32 v60, v2
	v_mov_b32_e32 v61, v2
	s_waitcnt vmcnt(22)
	v_mov_b32_e32 v62, v2
	v_mov_b32_e32 v63, v2
	v_mov_b32_e32 v64, v2
	v_mov_b32_e32 v65, v2
	v_mov_b32_e32 v66, v2
	v_mov_b32_e32 v67, v2
	v_mov_b32_e32 v68, v2
	v_mov_b32_e32 v69, v2
	v_mov_b32_e32 v70, v2
	v_mov_b32_e32 v71, v2
	v_mov_b32_e32 v72, v2
	v_mov_b32_e32 v73, v2
	v_mov_b32_e32 v82, v2
	v_mov_b32_e32 v83, v2
	v_mov_b32_e32 v84, v2
	v_mov_b32_e32 v85, v2
	v_mov_b32_e32 v86, v2
	v_mov_b32_e32 v87, v2
	v_mov_b32_e32 v88, v2
	v_mov_b32_e32 v89, v2
	v_mov_b32_e32 v98, v2
	v_mov_b32_e32 v99, v2
	v_mov_b32_e32 v100, v2
	v_mov_b32_e32 v101, v2
	v_mov_b32_e32 v102, v2
	v_mov_b32_e32 v103, v2
	v_mov_b32_e32 v104, v2
	v_mov_b32_e32 v105, v2
	v_mov_b32_e32 v122, v2
	v_mov_b32_e32 v123, v2
	v_mov_b32_e32 v124, v2
	v_mov_b32_e32 v125, v2
	v_mov_b32_e32 v126, v2
	v_mov_b32_e32 v127, v2
	v_mov_b32_e32 v128, v2
	v_mov_b32_e32 v129, v2
	v_mov_b32_e32 v74, v2
	v_mov_b32_e32 v75, v2
	v_mov_b32_e32 v76, v2
	v_mov_b32_e32 v77, v2
	v_mov_b32_e32 v78, v2
	v_mov_b32_e32 v79, v2
	v_mov_b32_e32 v80, v2
	v_mov_b32_e32 v81, v2
	v_mov_b32_e32 v90, v2
	v_mov_b32_e32 v91, v2
	v_mov_b32_e32 v92, v2
	v_mov_b32_e32 v93, v2
	v_mov_b32_e32 v94, v2
	v_mov_b32_e32 v95, v2
	v_mov_b32_e32 v96, v2
	v_mov_b32_e32 v97, v2
	v_mov_b32_e32 v110, v2
	v_mov_b32_e32 v111, v2
	v_mov_b32_e32 v112, v2
	v_mov_b32_e32 v113, v2
	v_mov_b32_e32 v114, v2
	v_mov_b32_e32 v115, v2
	v_mov_b32_e32 v116, v2
	v_mov_b32_e32 v117, v2
	v_mov_b32_e32 v134, v2
	v_mov_b32_e32 v135, v2
	v_mov_b32_e32 v136, v2
	v_mov_b32_e32 v137, v2
	v_mov_b32_e32 v142, v2
	v_mov_b32_e32 v143, v2
	v_mov_b32_e32 v144, v2
	v_mov_b32_e32 v145, v2
	.p2align	6

.LBB0_1380:
	s_lshl_b32 s68, s67, 21
	s_andn2_b64 vcc, exec, s[40:41]
	s_lshl_b32 s69, s66, 21
	s_cbranch_vccnz .LBB0_1388
	s_and_b64 s[14:15], s[4:5], exec
	v_mov_b32_e32 v2, 0
	s_cselect_b32 s72, s68, s74
	s_cselect_b32 s73, s69, s75
	s_add_i32 s74, s74, 0x180080
	s_addk_i32 s75, 0x100
	s_mov_b32 s76, 0
	v_mov_b32_e32 v3, v2
	v_mov_b32_e32 v4, v2
	v_mov_b32_e32 v5, v2
	s_waitcnt vmcnt(35)
	v_mov_b32_e32 v10, v2
	v_mov_b32_e32 v11, v2
	v_mov_b32_e32 v12, v2
	v_mov_b32_e32 v13, v2
	s_waitcnt vmcnt(33)
	v_mov_b32_e32 v18, v2
	v_mov_b32_e32 v19, v2
	v_mov_b32_e32 v20, v2
	v_mov_b32_e32 v21, v2
	s_waitcnt vmcnt(31)
	v_mov_b32_e32 v26, v2
	v_mov_b32_e32 v27, v2
	v_mov_b32_e32 v28, v2
	v_mov_b32_e32 v29, v2
	s_waitcnt vmcnt(29)
	v_mov_b32_e32 v34, v2
	v_mov_b32_e32 v35, v2
	v_mov_b32_e32 v36, v2
	v_mov_b32_e32 v37, v2
	s_waitcnt vmcnt(27)
	v_mov_b32_e32 v42, v2
	v_mov_b32_e32 v43, v2
	v_mov_b32_e32 v44, v2
	v_mov_b32_e32 v45, v2
	s_waitcnt vmcnt(25)
	v_mov_b32_e32 v50, v2
	v_mov_b32_e32 v51, v2
	v_mov_b32_e32 v52, v2
	v_mov_b32_e32 v53, v2
	s_waitcnt vmcnt(23)
	v_mov_b32_e32 v58, v2
	v_mov_b32_e32 v59, v2
	v_mov_b32_e32 v60, v2
	v_mov_b32_e32 v61, v2
	v_mov_b32_e32 v6, v2
	v_mov_b32_e32 v7, v2
	v_mov_b32_e32 v8, v2
	v_mov_b32_e32 v9, v2
	v_mov_b32_e32 v14, v2
	v_mov_b32_e32 v15, v2
	v_mov_b32_e32 v16, v2
	v_mov_b32_e32 v17, v2
	v_mov_b32_e32 v22, v2
	v_mov_b32_e32 v23, v2
	v_mov_b32_e32 v24, v2
	v_mov_b32_e32 v25, v2
	v_mov_b32_e32 v30, v2
	v_mov_b32_e32 v31, v2
	v_mov_b32_e32 v32, v2
	v_mov_b32_e32 v33, v2
	v_mov_b32_e32 v38, v2
	v_mov_b32_e32 v39, v2
	v_mov_b32_e32 v40, v2
	v_mov_b32_e32 v41, v2
	v_mov_b32_e32 v46, v2
	v_mov_b32_e32 v47, v2
	v_mov_b32_e32 v48, v2
	v_mov_b32_e32 v49, v2
	v_mov_b32_e32 v54, v2
	v_mov_b32_e32 v55, v2
	v_mov_b32_e32 v56, v2
	v_mov_b32_e32 v57, v2
	s_waitcnt vmcnt(22)
	v_mov_b32_e32 v62, v2
	v_mov_b32_e32 v63, v2
	v_mov_b32_e32 v64, v2
	v_mov_b32_e32 v65, v2
	v_mov_b32_e32 v70, v2
	v_mov_b32_e32 v71, v2
	v_mov_b32_e32 v72, v2
	v_mov_b32_e32 v73, v2
	v_mov_b32_e32 v74, v2
	v_mov_b32_e32 v75, v2
	v_mov_b32_e32 v76, v2
	v_mov_b32_e32 v77, v2
	v_mov_b32_e32 v82, v2
	v_mov_b32_e32 v83, v2
	v_mov_b32_e32 v84, v2
	v_mov_b32_e32 v85, v2
	v_mov_b32_e32 v90, v2
	v_mov_b32_e32 v91, v2
	v_mov_b32_e32 v92, v2
	v_mov_b32_e32 v93, v2
	v_mov_b32_e32 v98, v2
	v_mov_b32_e32 v99, v2
	v_mov_b32_e32 v100, v2
	v_mov_b32_e32 v101, v2
	v_mov_b32_e32 v106, v2
	v_mov_b32_e32 v107, v2
	v_mov_b32_e32 v108, v2
	v_mov_b32_e32 v109, v2
	v_mov_b32_e32 v122, v2
	v_mov_b32_e32 v123, v2
	v_mov_b32_e32 v124, v2
	v_mov_b32_e32 v125, v2
	v_mov_b32_e32 v126, v2
	v_mov_b32_e32 v127, v2
	v_mov_b32_e32 v128, v2
	v_mov_b32_e32 v129, v2
	v_mov_b32_e32 v66, v2
	v_mov_b32_e32 v67, v2
	v_mov_b32_e32 v68, v2
	v_mov_b32_e32 v69, v2
	v_mov_b32_e32 v78, v2
	v_mov_b32_e32 v79, v2
	v_mov_b32_e32 v80, v2
	v_mov_b32_e32 v81, v2
	v_mov_b32_e32 v86, v2
	v_mov_b32_e32 v87, v2
	v_mov_b32_e32 v88, v2
	v_mov_b32_e32 v89, v2
	v_mov_b32_e32 v94, v2
	v_mov_b32_e32 v95, v2
	v_mov_b32_e32 v96, v2
	v_mov_b32_e32 v97, v2
	v_mov_b32_e32 v102, v2
	v_mov_b32_e32 v103, v2
	v_mov_b32_e32 v104, v2
	v_mov_b32_e32 v105, v2
	v_mov_b32_e32 v110, v2
	v_mov_b32_e32 v111, v2
	v_mov_b32_e32 v112, v2
	v_mov_b32_e32 v113, v2
	v_mov_b32_e32 v114, v2
	v_mov_b32_e32 v115, v2
	v_mov_b32_e32 v116, v2
	v_mov_b32_e32 v117, v2
	v_mov_b32_e32 v118, v2
	v_mov_b32_e32 v119, v2
	v_mov_b32_e32 v120, v2
	v_mov_b32_e32 v121, v2
	.p2align	6

.LBB0_1400:
	s_lshl_b32 s69, s67, 21
	s_and_b64 vcc, exec, s[4:5]
	s_lshl_b32 s70, s68, 21
	s_cbranch_vccnz .LBB0_1408
	s_and_b64 s[22:23], s[6:7], exec
	v_mov_b32_e32 v2, 0
	s_cselect_b32 s73, s69, s75
	s_cselect_b32 s74, s70, s76
	s_add_i32 s75, s75, 0x180080
	s_addk_i32 s76, 0x100
	s_mov_b32 s77, 0
	v_mov_b32_e32 v3, v2
	v_mov_b32_e32 v4, v2
	v_mov_b32_e32 v5, v2
	s_waitcnt vmcnt(35)
	v_mov_b32_e32 v10, v2
	v_mov_b32_e32 v11, v2
	v_mov_b32_e32 v12, v2
	v_mov_b32_e32 v13, v2
	s_waitcnt vmcnt(33)
	v_mov_b32_e32 v18, v2
	v_mov_b32_e32 v19, v2
	v_mov_b32_e32 v20, v2
	v_mov_b32_e32 v21, v2
	s_waitcnt vmcnt(31)
	v_mov_b32_e32 v26, v2
	v_mov_b32_e32 v27, v2
	v_mov_b32_e32 v28, v2
	v_mov_b32_e32 v29, v2
	s_waitcnt vmcnt(29)
	v_mov_b32_e32 v34, v2
	v_mov_b32_e32 v35, v2
	v_mov_b32_e32 v36, v2
	v_mov_b32_e32 v37, v2
	s_waitcnt vmcnt(27)
	v_mov_b32_e32 v42, v2
	v_mov_b32_e32 v43, v2
	v_mov_b32_e32 v44, v2
	v_mov_b32_e32 v45, v2
	s_waitcnt vmcnt(25)
	v_mov_b32_e32 v50, v2
	v_mov_b32_e32 v51, v2
	v_mov_b32_e32 v52, v2
	v_mov_b32_e32 v53, v2
	s_waitcnt vmcnt(23)
	v_mov_b32_e32 v58, v2
	v_mov_b32_e32 v59, v2
	v_mov_b32_e32 v60, v2
	v_mov_b32_e32 v61, v2
	v_mov_b32_e32 v6, v2
	v_mov_b32_e32 v7, v2
	v_mov_b32_e32 v8, v2
	v_mov_b32_e32 v9, v2
	v_mov_b32_e32 v14, v2
	v_mov_b32_e32 v15, v2
	v_mov_b32_e32 v16, v2
	v_mov_b32_e32 v17, v2
	v_mov_b32_e32 v22, v2
	v_mov_b32_e32 v23, v2
	v_mov_b32_e32 v24, v2
	v_mov_b32_e32 v25, v2
	v_mov_b32_e32 v30, v2
	v_mov_b32_e32 v31, v2
	v_mov_b32_e32 v32, v2
	v_mov_b32_e32 v33, v2
	v_mov_b32_e32 v38, v2
	v_mov_b32_e32 v39, v2
	v_mov_b32_e32 v40, v2
	v_mov_b32_e32 v41, v2
	v_mov_b32_e32 v46, v2
	v_mov_b32_e32 v47, v2
	v_mov_b32_e32 v48, v2
	v_mov_b32_e32 v49, v2
	v_mov_b32_e32 v54, v2
	v_mov_b32_e32 v55, v2
	v_mov_b32_e32 v56, v2
	v_mov_b32_e32 v57, v2
	s_waitcnt vmcnt(22)
	v_mov_b32_e32 v62, v2
	v_mov_b32_e32 v63, v2
	v_mov_b32_e32 v64, v2
	v_mov_b32_e32 v65, v2
	v_mov_b32_e32 v70, v2
	v_mov_b32_e32 v71, v2
	v_mov_b32_e32 v72, v2
	v_mov_b32_e32 v73, v2
	v_mov_b32_e32 v74, v2
	v_mov_b32_e32 v75, v2
	v_mov_b32_e32 v76, v2
	v_mov_b32_e32 v77, v2
	v_mov_b32_e32 v82, v2
	v_mov_b32_e32 v83, v2
	v_mov_b32_e32 v84, v2
	v_mov_b32_e32 v85, v2
	v_mov_b32_e32 v90, v2
	v_mov_b32_e32 v91, v2
	v_mov_b32_e32 v92, v2
	v_mov_b32_e32 v93, v2
	v_mov_b32_e32 v98, v2
	v_mov_b32_e32 v99, v2
	v_mov_b32_e32 v100, v2
	v_mov_b32_e32 v101, v2
	v_mov_b32_e32 v106, v2
	v_mov_b32_e32 v107, v2
	v_mov_b32_e32 v108, v2
	v_mov_b32_e32 v109, v2
	v_mov_b32_e32 v122, v2
	v_mov_b32_e32 v123, v2
	v_mov_b32_e32 v124, v2
	v_mov_b32_e32 v125, v2
	v_mov_b32_e32 v126, v2
	v_mov_b32_e32 v127, v2
	v_mov_b32_e32 v128, v2
	v_mov_b32_e32 v129, v2
	v_mov_b32_e32 v66, v2
	v_mov_b32_e32 v67, v2
	v_mov_b32_e32 v68, v2
	v_mov_b32_e32 v69, v2
	v_mov_b32_e32 v78, v2
	v_mov_b32_e32 v79, v2
	v_mov_b32_e32 v80, v2
	v_mov_b32_e32 v81, v2
	v_mov_b32_e32 v86, v2
	v_mov_b32_e32 v87, v2
	v_mov_b32_e32 v88, v2
	v_mov_b32_e32 v89, v2
	v_mov_b32_e32 v94, v2
	v_mov_b32_e32 v95, v2
	v_mov_b32_e32 v96, v2
	v_mov_b32_e32 v97, v2
	v_mov_b32_e32 v102, v2
	v_mov_b32_e32 v103, v2
	v_mov_b32_e32 v104, v2
	v_mov_b32_e32 v105, v2
	v_mov_b32_e32 v110, v2
	v_mov_b32_e32 v111, v2
	v_mov_b32_e32 v112, v2
	v_mov_b32_e32 v113, v2
	v_mov_b32_e32 v114, v2
	v_mov_b32_e32 v115, v2
	v_mov_b32_e32 v116, v2
	v_mov_b32_e32 v117, v2
	v_mov_b32_e32 v118, v2
	v_mov_b32_e32 v119, v2
	v_mov_b32_e32 v120, v2
	v_mov_b32_e32 v121, v2
	.p2align	6

.LBB0_1517:
	s_mul_i32 s76, s75, 0x560000
	s_andn2_b64 vcc, exec, s[36:37]
	s_mul_i32 s77, s74, 0x560000
	s_cbranch_vccnz .LBB0_1543
	s_and_b64 s[6:7], s[4:5], exec
	v_mov_b32_e32 v2, 0
	s_cselect_b32 s6, s76, s80
	s_cselect_b32 s7, s77, s81
	s_add_i32 s80, s80, 0x408080
	s_addk_i32 s81, 0x100
	s_mov_b32 s82, 0
	s_waitcnt lgkmcnt(0)
	v_mov_b32_e32 v3, v2
	v_mov_b32_e32 v4, v2
	v_mov_b32_e32 v5, v2
	v_mov_b32_e32 v6, v2
	v_mov_b32_e32 v7, v2
	v_mov_b32_e32 v8, v2
	v_mov_b32_e32 v9, v2
	s_waitcnt vmcnt(35)
	v_mov_b32_e32 v10, v2
	v_mov_b32_e32 v11, v2
	v_mov_b32_e32 v12, v2
	v_mov_b32_e32 v13, v2
	s_waitcnt vmcnt(34)
	v_mov_b32_e32 v14, v2
	v_mov_b32_e32 v15, v2
	v_mov_b32_e32 v16, v2
	v_mov_b32_e32 v17, v2
	s_waitcnt vmcnt(32)
	v_mov_b32_e32 v22, v2
	v_mov_b32_e32 v23, v2
	v_mov_b32_e32 v24, v2
	v_mov_b32_e32 v25, v2
	s_waitcnt vmcnt(30)
	v_mov_b32_e32 v30, v2
	v_mov_b32_e32 v31, v2
	v_mov_b32_e32 v32, v2
	v_mov_b32_e32 v33, v2
	s_waitcnt vmcnt(28)
	v_mov_b32_e32 v38, v2
	v_mov_b32_e32 v39, v2
	v_mov_b32_e32 v40, v2
	v_mov_b32_e32 v41, v2
	s_waitcnt vmcnt(26)
	v_mov_b32_e32 v46, v2
	v_mov_b32_e32 v47, v2
	v_mov_b32_e32 v48, v2
	v_mov_b32_e32 v49, v2
	v_mov_b32_e32 v18, v2
	v_mov_b32_e32 v19, v2
	v_mov_b32_e32 v20, v2
	v_mov_b32_e32 v21, v2
	v_mov_b32_e32 v26, v2
	v_mov_b32_e32 v27, v2
	v_mov_b32_e32 v28, v2
	v_mov_b32_e32 v29, v2
	v_mov_b32_e32 v34, v2
	v_mov_b32_e32 v35, v2
	v_mov_b32_e32 v36, v2
	v_mov_b32_e32 v37, v2
	v_mov_b32_e32 v42, v2
	v_mov_b32_e32 v43, v2
	v_mov_b32_e32 v44, v2
	v_mov_b32_e32 v45, v2
	s_waitcnt vmcnt(25)
	v_mov_b32_e32 v50, v2
	v_mov_b32_e32 v51, v2
	v_mov_b32_e32 v52, v2
	v_mov_b32_e32 v53, v2
	s_waitcnt vmcnt(24)
	v_mov_b32_e32 v54, v2
	v_mov_b32_e32 v55, v2
	v_mov_b32_e32 v56, v2
	v_mov_b32_e32 v57, v2
	s_waitcnt vmcnt(23)
	v_mov_b32_e32 v58, v2
	v_mov_b32_e32 v59, v2
	v_mov_b32_e32 v60, v2
	v_mov_b32_e32 v61, v2
	s_waitcnt vmcnt(22)
	v_mov_b32_e32 v62, v2
	v_mov_b32_e32 v63, v2
	v_mov_b32_e32 v64, v2
	v_mov_b32_e32 v65, v2
	v_mov_b32_e32 v66, v2
	v_mov_b32_e32 v67, v2
	v_mov_b32_e32 v68, v2
	v_mov_b32_e32 v69, v2
	v_mov_b32_e32 v70, v2
	v_mov_b32_e32 v71, v2
	v_mov_b32_e32 v72, v2
	v_mov_b32_e32 v73, v2
	v_mov_b32_e32 v74, v2
	v_mov_b32_e32 v75, v2
	v_mov_b32_e32 v76, v2
	v_mov_b32_e32 v77, v2
	v_mov_b32_e32 v78, v2
	v_mov_b32_e32 v79, v2
	v_mov_b32_e32 v80, v2
	v_mov_b32_e32 v81, v2
	v_mov_b32_e32 v86, v2
	v_mov_b32_e32 v87, v2
	v_mov_b32_e32 v88, v2
	v_mov_b32_e32 v89, v2
	v_mov_b32_e32 v94, v2
	v_mov_b32_e32 v95, v2
	v_mov_b32_e32 v96, v2
	v_mov_b32_e32 v97, v2
	v_mov_b32_e32 v102, v2
	v_mov_b32_e32 v103, v2
	v_mov_b32_e32 v104, v2
	v_mov_b32_e32 v105, v2
	v_mov_b32_e32 v110, v2
	v_mov_b32_e32 v111, v2
	v_mov_b32_e32 v112, v2
	v_mov_b32_e32 v113, v2
	v_mov_b32_e32 v82, v2
	v_mov_b32_e32 v83, v2
	v_mov_b32_e32 v84, v2
	v_mov_b32_e32 v85, v2
	v_mov_b32_e32 v90, v2
	v_mov_b32_e32 v91, v2
	v_mov_b32_e32 v92, v2
	v_mov_b32_e32 v93, v2
	v_mov_b32_e32 v98, v2
	v_mov_b32_e32 v99, v2
	v_mov_b32_e32 v100, v2
	v_mov_b32_e32 v101, v2
	v_mov_b32_e32 v106, v2
	v_mov_b32_e32 v107, v2
	v_mov_b32_e32 v108, v2
	v_mov_b32_e32 v109, v2
	v_mov_b32_e32 v114, v2
	v_mov_b32_e32 v115, v2
	v_mov_b32_e32 v116, v2
	v_mov_b32_e32 v117, v2
	v_mov_b32_e32 v118, v2
	v_mov_b32_e32 v119, v2
	v_mov_b32_e32 v120, v2
	v_mov_b32_e32 v121, v2
	v_mov_b32_e32 v122, v2
	v_mov_b32_e32 v123, v2
	v_mov_b32_e32 v124, v2
	v_mov_b32_e32 v125, v2
	v_mov_b32_e32 v126, v2
	v_mov_b32_e32 v127, v2
	v_mov_b32_e32 v128, v2
	v_mov_b32_e32 v129, v2
	.p2align	6
